# HB2 (mlp1 A operand) stored row-pair interleaved so each LDS-DMA row request covers a full 128B line; mlp1 k-loop software-pipelined (on top of scan rewrite)
# speedup vs baseline: 1.0234x; 1.0159x over previous
; template <int MI, int NI>
; DI void gemm256(f32x4 (&acc)[MI][NI], const u16* __restrict__ A, int lda, const u16* __restrict__ Bt, int ldb, int K, int m0, int n0, char* smem) {
;     ...
;   const int srow = lane >> 2, scol = ((lane & 3) ^ ((lane >> 5) << 1)) * 8;
;   const u16* Ag = A + (size_t)(m0 + wave * NAW * 16 + srow) * lda + scol;
;   const u16* Bg = Bt + (size_t)(n0 + wave * NBW * 16 + srow) * ldb + scol;
;   char* la = smem + (wave * NAW) * 1024 + lane * 16;
;   char* lb = smem + ABYTES + (wave * NBW) * 1024 + lane * 16;
;     ...
;   const int nk = K >> 5;
;   G256_ISSUE(0, 0);
;   if (nk > 1) G256_ISSUE(1, 32);
; DI void phase_mlp1(const Params& p, int l, int Mout, char* smem) {
;     ...
;   for (int it = 0;; ++it) {
;     int tm, tn;
;     if (!tile_map(it, ntm, 32, blk__, gridDim.x, tm, tn)) break;
;     const int m0 = tm * 256, n0 = tn * 128;
;     f32x4 acc[8][4]; zero_accm<8, 4>(acc);
;     gemm256<8, 4>(acc, hb, 1024, (const u16*)(wl + WO_W1), 1024, 1024, m0, n0, smem);
.LBB0_444:
	s_lshl_b32 s12, s4, 3
	v_cvt_f32_u32_e32 v0, s12
	s_sub_i32 s11, 0, s12
	s_sub_i32 s9, s9, s10
	s_abs_i32 s10, s9
	v_rcp_iflag_f32_e32 v0, v0
	s_ashr_i32 s13, s9, 31
	s_waitcnt vmcnt(0)
	v_mov_b32_e32 v8, v163
	v_mul_f32_e32 v0, 0x4f7ffffe, v0
	v_cvt_u32_f32_e32 v0, v0
	v_lshrrev_b32_e32 v2, 4, v8
	v_and_b32_e32 v10, 0xffffffc0, v8
	v_ashrrev_i32_e32 v7, 6, v8
	v_readfirstlane_b32 s14, v0
	s_mul_i32 s11, s11, s14
	s_mul_hi_u32 s11, s14, s11
	s_add_i32 s14, s14, s11
	s_mul_hi_u32 s11, s10, s14
	s_mul_i32 s14, s11, s12
	s_sub_i32 s10, s10, s14
	s_add_i32 s15, s11, 1
	s_sub_i32 s14, s10, s12
	s_cmp_ge_u32 s10, s12
	s_cselect_b32 s11, s15, s11
	s_cselect_b32 s10, s14, s10
	s_add_i32 s14, s11, 1
	s_cmp_ge_u32 s10, s12
	s_cselect_b32 s10, s14, s11
	s_abs_i32 s14, s4
	v_cvt_f32_u32_e32 v0, s14
	s_xor_b32 s15, s10, s13
	s_sub_i32 s10, 0, s14
	s_sub_i32 s16, s15, s13
	v_rcp_iflag_f32_e32 v0, v0
	s_mul_i32 s12, s16, s12
	s_sub_i32 s9, s9, s12
	s_abs_i32 s17, s9
	v_mul_f32_e32 v0, 0x4f7ffffe, v0
	v_cvt_u32_f32_e32 v0, v0
	s_xor_b32 s12, s9, s4
	s_ashr_i32 s12, s12, 31
	v_bfe_u32 v9, v8, 2, 4
	v_readfirstlane_b32 s18, v0
	s_mul_i32 s10, s10, s18
	s_mul_hi_u32 s10, s18, s10
	s_add_i32 s18, s18, s10
	s_mul_hi_u32 s10, s17, s18
	s_mul_i32 s18, s10, s14
	s_sub_i32 s17, s17, s18
	s_add_i32 s19, s10, 1
	s_sub_i32 s18, s17, s14
	s_cmp_ge_u32 s17, s14
	s_cselect_b32 s10, s19, s10
	s_cselect_b32 s17, s18, s17
	s_add_i32 s18, s10, 1
	s_cmp_ge_u32 s17, s14
	s_cselect_b32 s10, s18, s10
	s_xor_b32 s14, s10, s12
	s_sub_i32 s17, s14, s12
	s_mul_i32 s4, s17, s4
	s_add_i32 s5, s5, s7
	s_sub_i32 s4, s9, s4
	s_add_i32 s5, s5, s4
	s_lshl_b32 s10, s5, 8
	s_lshl_b32 s4, s16, 10
	s_lshl_b32 s9, s17, 7
	v_and_b32_e32 v0, 3, v8
	s_add_i32 s9, s9, s4
	s_mov_b32 s4, s2
	v_bitop3_b32 v0, v2, v0, 2 bitop3:0x6c
	v_add_u32_e32 v2, s10, v10
	v_or_b32_e32 v2, v2, v9
	v_lshlrev_b32_e32 v11, 5, v7
	v_ashrrev_i32_e32 v3, 31, v2
	v_readlane_b32 s4, v253, 39
	v_add_u32_e32 v4, s9, v11
	v_and_b32_e32 v6, 63, v8
	v_lshlrev_b64 v[2:3], 11, v[2:3]
	v_readlane_b32 s5, v253, 40
	v_or_b32_e32 v4, v4, v9
	v_ashrrev_i32_e32 v5, 31, v4
	v_lshl_add_u64 v[2:3], s[4:5], 0, v[2:3]
	v_readlane_b32 s4, v253, 44
	v_lshlrev_b32_e32 v12, 12, v7
	v_lshlrev_b32_e32 v6, 4, v6
	v_lshlrev_b64 v[4:5], 11, v[4:5]
	v_readlane_b32 s5, v253, 45
	v_or_b32_e32 v138, v12, v6
	v_lshlrev_b32_e32 v0, 4, v0
	v_lshl_add_u64 v[4:5], s[4:5], 0, v[4:5]
	v_readfirstlane_b32 s4, v138
	v_or_b32_e32 v14, 0x400, v138
	v_lshl_add_u64 v[2:3], v[2:3], 0, v[0:1]
	v_bfe_i32 v199, v163, 2, 1
	v_and_b32_e32 v198, 0xfffff840, v199
	v_lshl_add_u64 v[2:3], v[2:3], 0, v[198:199]
	s_mov_b32 m0, s4
	v_readfirstlane_b32 s4, v14
	v_lshl_or_b32 v139, v7, 11, v6
	global_load_lds_dwordx4 v[2:3], off
	v_lshl_add_u64 v[6:7], v[2:3], 0, s[68:69]
	s_mov_b32 m0, s4
	s_mov_b64 s[4:5], 0x10000
	v_or_b32_e32 v14, 0x800, v138
	global_load_lds_dwordx4 v[6:7], off
	v_lshl_add_u64 v[6:7], v[2:3], 0, s[4:5]
	v_readfirstlane_b32 s4, v14
	s_mov_b32 m0, s4
	s_mov_b64 s[4:5], 0x18000
	v_or_b32_e32 v14, 0xc00, v138
	v_add_u32_e32 v13, 0x4000, v139
	global_load_lds_dwordx4 v[6:7], off
	v_lshl_add_u64 v[6:7], v[2:3], 0, s[4:5]
	v_readfirstlane_b32 s4, v14
	s_mov_b32 m0, s4
	v_readfirstlane_b32 s4, v13
	v_add_u32_e32 v13, 0x4400, v139
	global_load_lds_dwordx4 v[6:7], off
	v_lshl_add_u64 v[4:5], v[4:5], 0, v[0:1]
	s_mov_b32 m0, s4
	v_readfirstlane_b32 s4, v13
	v_add_u32_e32 v13, 0x6000, v138
	global_load_lds_dwordx4 v[4:5], off
	v_lshl_add_u64 v[6:7], v[4:5], 0, s[68:69]
	s_mov_b32 m0, s4
	v_readfirstlane_b32 s4, v13
	v_add_u32_e32 v13, 0x6400, v138
	global_load_lds_dwordx4 v[6:7], off
	s_mov_b64 s[98:99], 0x80
	v_lshl_add_u64 v[6:7], v[2:3], 0, s[98:99]
	s_mov_b32 m0, s4
	v_readfirstlane_b32 s4, v13
	global_load_lds_dwordx4 v[6:7], off
	s_mov_b64 s[98:99], 0x8080
	v_lshl_add_u64 v[6:7], v[2:3], 0, s[98:99]
	s_mov_b32 m0, s4
	s_mov_b64 s[4:5], 0x10080
	v_add_u32_e32 v13, 0x6800, v138
	global_load_lds_dwordx4 v[6:7], off
	v_lshl_add_u64 v[6:7], v[2:3], 0, s[4:5]
	v_readfirstlane_b32 s4, v13
	s_mov_b32 m0, s4
	s_mov_b64 s[4:5], 0x18080
	global_load_lds_dwordx4 v[6:7], off
	v_add_u32_e32 v6, 0x6c00, v138
	v_lshl_add_u64 v[2:3], v[2:3], 0, s[4:5]
	v_readfirstlane_b32 s4, v6
	v_add_u32_e32 v6, 0xa000, v139
	s_mov_b32 m0, s4
	v_readfirstlane_b32 s4, v6
	global_load_lds_dwordx4 v[2:3], off
	v_lshl_add_u64 v[2:3], v[4:5], 0, 64
	s_mov_b32 m0, s4
	s_lshl_b32 s5, s14, 7
	global_load_lds_dwordx4 v[2:3], off
	v_lshl_add_u64 v[2:3], v[4:5], 0, s[74:75]
	v_add_u32_e32 v4, 0xa400, v139
	s_mov_b32 s11, 0
	v_readfirstlane_b32 s4, v4
	s_mov_b32 m0, s4
	v_and_b32_e32 v4, 48, v8
	global_load_lds_dwordx4 v[2:3], off
	v_lshlrev_b32_e32 v3, 2, v8
	s_lshl_b32 s4, s15, 10
	v_lshlrev_b32_e32 v2, 6, v8
	v_bitop3_b32 v3, v3, v4, 32 bitop3:0x6c
	s_add_i32 s5, s5, s4
	v_and_or_b32 v140, v2, s59, v3
	v_and_b32_e32 v142, 0xffffe000, v2
	v_or_b32_e32 v2, s5, v9
	v_add_u32_e32 v2, v2, v11
	s_lshl_b32 s4, s12, 7
	v_subrev_u32_e32 v2, s4, v2
	s_lshl_b32 s4, s13, 10
	v_subrev_u32_e32 v2, s4, v2
	v_ashrrev_i32_e32 v3, 31, v2
	v_lshlrev_b64 v[2:3], 11, v[2:3]
	v_readlane_b32 s4, v254, 52
	v_or_b32_e32 v2, v2, v0
	v_readlane_b32 s5, v254, 53
	v_and_b32_e32 v141, 0x1000, v12
	s_nop 0
	v_lshl_add_u64 v[130:131], s[4:5], 0, v[2:3]
	v_or_b32_e32 v2, s10, v9
	v_add_u32_e32 v2, v2, v10
	v_ashrrev_i32_e32 v3, 31, v2
	v_lshlrev_b64 v[2:3], 11, v[2:3]
	v_or_b32_e32 v2, v2, v0
	v_lshl_add_u64 v[132:133], s[62:63], 0, v[2:3]
	v_mov_b32_e32 v2, 0
	s_mov_b64 s[4:5], 0
	v_mov_b32_e32 v3, v2
	v_mov_b32_e32 v4, v2
	v_mov_b32_e32 v5, v2
	v_mov_b32_e32 v6, v2
	v_mov_b32_e32 v7, v2
	v_mov_b32_e32 v8, v2
	v_mov_b32_e32 v9, v2
	v_mov_b32_e32 v10, v2
	v_mov_b32_e32 v11, v2
	v_mov_b32_e32 v12, v2
	v_mov_b32_e32 v13, v2
	v_mov_b32_e32 v14, v2
	v_mov_b32_e32 v15, v2
	v_mov_b32_e32 v16, v2
	v_mov_b32_e32 v17, v2
	v_mov_b32_e32 v18, v2
	v_mov_b32_e32 v19, v2
	v_mov_b32_e32 v20, v2
	v_mov_b32_e32 v21, v2
	v_mov_b32_e32 v22, v2
	v_mov_b32_e32 v23, v2
	v_mov_b32_e32 v24, v2
	v_mov_b32_e32 v25, v2
	s_waitcnt lgkmcnt(0)
; template <int MI, int NI>
; DI void gemm256(f32x4 (&acc)[MI][NI], const u16* __restrict__ A, int lda, const u16* __restrict__ Bt, int ldb, int K, int m0, int n0, char* smem) {
;     ...
;   for (int kt = 0; kt < nk; ++kt) {
;     if (kt + 1 < nk) asm volatile("s_waitcnt vmcnt(%0) lgkmcnt(0)" :: "n"(LPS) : "memory");
;     else asm volatile("s_waitcnt vmcnt(0) lgkmcnt(0)" ::: "memory");
;     __builtin_amdgcn_s_barrier();
;     __builtin_amdgcn_s_setprio(1);
;     const char* sb = smem + st * STAGE + foff;
;     bf16x8 af[MI], bfr[NI];
; #pragma unroll
;     for (int mi = 0; mi < MI; ++mi) af[mi] = *(const bf16x8*)(sb + (wr * MI + mi) * 1024);
; #pragma unroll
;     for (int ni = 0; ni < NI; ++ni) bfr[ni] = *(const bf16x8*)(sb + ABYTES + (wc * NI + ni) * 1024);
;     __builtin_amdgcn_sched_barrier(0x0);
;     if (kt + 2 < nk) { const int s2 = st >= 1 ? st - 1 : 2; G256_ISSUE(s2, (kt + 2) * 32); }
;     __builtin_amdgcn_s_setprio(0);
; #pragma unroll
;     for (int mi = 0; mi < MI; ++mi)
; #pragma unroll
;       for (int ni = 0; ni < NI; ++ni)
;         acc[mi][ni] = __builtin_amdgcn_mfma_f32_16x16x32_bf16(bfr[ni], af[mi], acc[mi][ni], 0, 0, 0);
;     st = st == 2 ? 0 : st + 1;
;   }
; template <int MI, int NI>
; DI void zero_accm(f32x4 (&acc)[MI][NI]) {
; #pragma unroll
;   for (int i = 0; i < MI; ++i)
; #pragma unroll
;     for (int j = 0; j < NI; ++j) acc[i][j] = f32x4{0.f, 0.f, 0.f, 0.f};
; }
	v_mov_b32_e32 v26, v2
	v_mov_b32_e32 v27, v2
	v_mov_b32_e32 v28, v2
	v_mov_b32_e32 v29, v2
	v_mov_b32_e32 v30, v2
	v_mov_b32_e32 v31, v2
	v_mov_b32_e32 v32, v2
	v_mov_b32_e32 v33, v2
	v_mov_b32_e32 v34, v2
	v_mov_b32_e32 v35, v2
	v_mov_b32_e32 v36, v2
	v_mov_b32_e32 v37, v2
	v_mov_b32_e32 v38, v2
	v_mov_b32_e32 v39, v2
	v_mov_b32_e32 v40, v2
	v_mov_b32_e32 v41, v2
	v_mov_b32_e32 v42, v2
	v_mov_b32_e32 v43, v2
	v_mov_b32_e32 v44, v2
	v_mov_b32_e32 v45, v2
	v_mov_b32_e32 v46, v2
	v_mov_b32_e32 v47, v2
	v_mov_b32_e32 v48, v2
	v_mov_b32_e32 v49, v2
	v_mov_b32_e32 v50, v2
	v_mov_b32_e32 v51, v2
	v_mov_b32_e32 v52, v2
	v_mov_b32_e32 v53, v2
	v_mov_b32_e32 v54, v2
	v_mov_b32_e32 v55, v2
	v_mov_b32_e32 v56, v2
	v_mov_b32_e32 v57, v2
	v_mov_b32_e32 v58, v2
	v_mov_b32_e32 v59, v2
	v_mov_b32_e32 v60, v2
	v_mov_b32_e32 v61, v2
	v_mov_b32_e32 v62, v2
	v_mov_b32_e32 v63, v2
	v_mov_b32_e32 v64, v2
	v_mov_b32_e32 v65, v2
	v_mov_b32_e32 v66, v2
	v_mov_b32_e32 v67, v2
	v_mov_b32_e32 v68, v2
	v_mov_b32_e32 v69, v2
	v_mov_b32_e32 v70, v2
	v_mov_b32_e32 v71, v2
	v_mov_b32_e32 v72, v2
	v_mov_b32_e32 v73, v2
	v_mov_b32_e32 v74, v2
	v_mov_b32_e32 v75, v2
	v_mov_b32_e32 v76, v2
	v_mov_b32_e32 v77, v2
	v_mov_b32_e32 v78, v2
	v_mov_b32_e32 v79, v2
	v_mov_b32_e32 v80, v2
	v_mov_b32_e32 v81, v2
	v_mov_b32_e32 v82, v2
	v_mov_b32_e32 v83, v2
	v_mov_b32_e32 v84, v2
	v_mov_b32_e32 v85, v2
	v_mov_b32_e32 v86, v2
	v_mov_b32_e32 v87, v2
	v_mov_b32_e32 v88, v2
	v_mov_b32_e32 v89, v2
	v_mov_b32_e32 v90, v2
	v_mov_b32_e32 v91, v2
	v_mov_b32_e32 v92, v2
	v_mov_b32_e32 v93, v2
	v_mov_b32_e32 v94, v2
	v_mov_b32_e32 v95, v2
	v_mov_b32_e32 v96, v2
	v_mov_b32_e32 v97, v2
	v_mov_b32_e32 v98, v2
	v_mov_b32_e32 v99, v2
	v_mov_b32_e32 v100, v2
	v_mov_b32_e32 v101, v2
	v_mov_b32_e32 v102, v2
	v_mov_b32_e32 v103, v2
	v_mov_b32_e32 v104, v2
	v_mov_b32_e32 v105, v2
	v_mov_b32_e32 v106, v2
	v_mov_b32_e32 v107, v2
	v_mov_b32_e32 v108, v2
	v_mov_b32_e32 v109, v2
	v_mov_b32_e32 v110, v2
	v_mov_b32_e32 v111, v2
	v_mov_b32_e32 v112, v2
	v_mov_b32_e32 v113, v2
	v_mov_b32_e32 v114, v2
	v_mov_b32_e32 v115, v2
	v_mov_b32_e32 v116, v2
	v_mov_b32_e32 v117, v2
	v_mov_b32_e32 v118, v2
	v_mov_b32_e32 v119, v2
	v_mov_b32_e32 v120, v2
	v_mov_b32_e32 v121, v2
	v_mov_b32_e32 v122, v2
	v_mov_b32_e32 v123, v2
	v_mov_b32_e32 v124, v2
	v_mov_b32_e32 v125, v2
	v_mov_b32_e32 v126, v2
	v_mov_b32_e32 v127, v2
	v_mov_b32_e32 v128, v2
	v_mov_b32_e32 v129, v2
	s_mov_b64 s[12:13], 0x16281100
	v_lshl_add_u64 v[198:199], v[132:133], 0, s[12:13]
	s_mov_b64 s[12:13], 0x16289100
	v_lshl_add_u64 v[200:201], v[132:133], 0, s[12:13]
	s_mov_b64 s[12:13], 0x16291100
	v_lshl_add_u64 v[202:203], v[132:133], 0, s[12:13]
	s_mov_b64 s[12:13], 0x16299100
	v_lshl_add_u64 v[204:205], v[132:133], 0, s[12:13]
	s_mov_b64 s[12:13], 0x1861080
	v_lshl_add_u64 v[206:207], v[130:131], 0, s[12:13]
	s_mov_b64 s[12:13], 0x1869080
	v_lshl_add_u64 v[208:209], v[130:131], 0, s[12:13]
	v_bfe_i32 v197, v163, 2, 1
	v_and_b32_e32 v196, 0xfffff840, v197
	v_lshl_add_u64 v[198:199], v[198:199], 0, v[196:197]
	v_lshl_add_u64 v[200:201], v[200:201], 0, v[196:197]
	v_lshl_add_u64 v[202:203], v[202:203], 0, v[196:197]
	v_lshl_add_u64 v[204:205], v[204:205], 0, v[196:197]
	s_mov_b64 s[98:99], 0x80
	v_add_u32_e32 v143, v140, v142
	v_add_u32_e32 v0, v140, v141
	v_readfirstlane_b32 s14, v138
	v_readfirstlane_b32 s4, v139
	s_mov_b32 s11, 0
	s_movk_i32 s5, 29
	s_add_i32 s4, s4, 0x4000
	s_waitcnt vmcnt(6) lgkmcnt(0)
	s_barrier
	ds_read_b128 v[144:147], v143
	ds_read_b128 v[148:151], v143 offset:1024
	ds_read_b128 v[152:155], v143 offset:2048
	ds_read_b128 v[156:159], v143 offset:3072
	ds_read_b128 v[180:183], v0 offset:16384
	ds_read_b128 v[184:187], v0 offset:17408
	ds_read_b128 v[188:191], v0 offset:18432
	ds_read_b128 v[192:195], v0 offset:19456
.Lpipe_mlp1:
	v_add_u32_e32 v160, s11, v143
	ds_read_b128 v[164:167], v160 offset:4096
	ds_read_b128 v[168:171], v160 offset:5120
	ds_read_b128 v[172:175], v160 offset:6144
	ds_read_b128 v[176:179], v160 offset:7168
	s_add_i32 s12, s11, 0xffffa000
	s_cmp_eq_u32 s11, 0
	s_cselect_b32 s12, 0xc000, s12
	s_add_i32 s13, s12, s14
	s_add_i32 s12, s12, s4
	s_mov_b32 m0, s13
	s_waitcnt lgkmcnt(7)
	v_mfma_f32_16x16x32_bf16 v[126:129], v[180:183], v[144:147], v[126:129]
	global_load_lds_dwordx4 v[198:199], off
	v_mfma_f32_16x16x32_bf16 v[110:113], v[180:183], v[148:151], v[110:113]
	v_lshl_add_u64 v[198:199], v[198:199], 0, s[98:99]
	s_add_i32 m0, s13, 0x400
	v_mfma_f32_16x16x32_bf16 v[94:97], v[180:183], v[152:155], v[94:97]
	global_load_lds_dwordx4 v[200:201], off
	v_mfma_f32_16x16x32_bf16 v[78:81], v[180:183], v[156:159], v[78:81]
	v_lshl_add_u64 v[200:201], v[200:201], 0, s[98:99]
	s_add_i32 m0, s13, 0x800
	s_waitcnt lgkmcnt(6)
	v_mfma_f32_16x16x32_bf16 v[122:125], v[184:187], v[144:147], v[122:125]
	global_load_lds_dwordx4 v[202:203], off
	v_mfma_f32_16x16x32_bf16 v[106:109], v[184:187], v[148:151], v[106:109]
	v_lshl_add_u64 v[202:203], v[202:203], 0, s[98:99]
	s_add_i32 m0, s13, 0xc00
	v_mfma_f32_16x16x32_bf16 v[90:93], v[184:187], v[152:155], v[90:93]
	global_load_lds_dwordx4 v[204:205], off
	v_mfma_f32_16x16x32_bf16 v[74:77], v[184:187], v[156:159], v[74:77]
	v_lshl_add_u64 v[204:205], v[204:205], 0, s[98:99]
	s_mov_b32 m0, s12
	s_waitcnt lgkmcnt(5)
	v_mfma_f32_16x16x32_bf16 v[118:121], v[188:191], v[144:147], v[118:121]
	global_load_lds_dwordx4 v[206:207], off
	v_mfma_f32_16x16x32_bf16 v[102:105], v[188:191], v[148:151], v[102:105]
	v_lshl_add_u64 v[206:207], v[206:207], 0, 64
	s_add_i32 m0, s12, 0x400
	v_mfma_f32_16x16x32_bf16 v[86:89], v[188:191], v[152:155], v[86:89]
	global_load_lds_dwordx4 v[208:209], off
	v_mfma_f32_16x16x32_bf16 v[70:73], v[188:191], v[156:159], v[70:73]
	v_lshl_add_u64 v[208:209], v[208:209], 0, 64
	s_waitcnt lgkmcnt(4)
	v_mfma_f32_16x16x32_bf16 v[114:117], v[192:195], v[144:147], v[114:117]
	v_mfma_f32_16x16x32_bf16 v[98:101], v[192:195], v[148:151], v[98:101]
	v_mfma_f32_16x16x32_bf16 v[82:85], v[192:195], v[152:155], v[82:85]
	v_mfma_f32_16x16x32_bf16 v[66:69], v[192:195], v[156:159], v[66:69]
	s_waitcnt vmcnt(6) lgkmcnt(0)
	s_barrier
; template <int MI, int NI>
; DI void gemm256(f32x4 (&acc)[MI][NI], const u16* __restrict__ A, int lda, const u16* __restrict__ Bt, int ldb, int K, int m0, int n0, char* smem) {
;     ...
;   for (int kt = 0; kt < nk; ++kt) {
;     if (kt + 1 < nk) asm volatile("s_waitcnt vmcnt(%0) lgkmcnt(0)" :: "n"(LPS) : "memory");
;     else asm volatile("s_waitcnt vmcnt(0) lgkmcnt(0)" ::: "memory");
;     __builtin_amdgcn_s_barrier();
;     __builtin_amdgcn_s_setprio(1);
;     const char* sb = smem + st * STAGE + foff;
;     bf16x8 af[MI], bfr[NI];
; #pragma unroll
;     for (int mi = 0; mi < MI; ++mi) af[mi] = *(const bf16x8*)(sb + (wr * MI + mi) * 1024);
; #pragma unroll
;     for (int ni = 0; ni < NI; ++ni) bfr[ni] = *(const bf16x8*)(sb + ABYTES + (wc * NI + ni) * 1024);
;     __builtin_amdgcn_sched_barrier(0x0);
;     if (kt + 2 < nk) { const int s2 = st >= 1 ? st - 1 : 2; G256_ISSUE(s2, (kt + 2) * 32); }
;     __builtin_amdgcn_s_setprio(0);
; #pragma unroll
;     for (int mi = 0; mi < MI; ++mi)
; #pragma unroll
;       for (int ni = 0; ni < NI; ++ni)
;         acc[mi][ni] = __builtin_amdgcn_mfma_f32_16x16x32_bf16(bfr[ni], af[mi], acc[mi][ni], 0, 0, 0);
;     st = st == 2 ? 0 : st + 1;
;   }
	s_add_i32 s13, s11, 0x6000
	s_cmp_eq_u32 s11, 0xc000
	s_cselect_b32 s11, 0, s13
	v_add_u32_e32 v196, s11, v143
	v_add_u32_e32 v197, s11, v0
	v_mfma_f32_16x16x32_bf16 v[62:65], v[180:183], v[164:167], v[62:65]
	ds_read_b128 v[144:147], v196
	v_mfma_f32_16x16x32_bf16 v[46:49], v[180:183], v[168:171], v[46:49]
	ds_read_b128 v[148:151], v196 offset:1024
	v_mfma_f32_16x16x32_bf16 v[30:33], v[180:183], v[172:175], v[30:33]
	ds_read_b128 v[152:155], v196 offset:2048
	v_mfma_f32_16x16x32_bf16 v[14:17], v[180:183], v[176:179], v[14:17]
	ds_read_b128 v[156:159], v196 offset:3072
	ds_read_b128 v[180:183], v197 offset:16384
	v_mfma_f32_16x16x32_bf16 v[58:61], v[184:187], v[164:167], v[58:61]
	v_mfma_f32_16x16x32_bf16 v[42:45], v[184:187], v[168:171], v[42:45]
	v_mfma_f32_16x16x32_bf16 v[26:29], v[184:187], v[172:175], v[26:29]
	v_mfma_f32_16x16x32_bf16 v[10:13], v[184:187], v[176:179], v[10:13]
	ds_read_b128 v[184:187], v197 offset:17408
	v_mfma_f32_16x16x32_bf16 v[54:57], v[188:191], v[164:167], v[54:57]
	v_mfma_f32_16x16x32_bf16 v[38:41], v[188:191], v[168:171], v[38:41]
	v_mfma_f32_16x16x32_bf16 v[22:25], v[188:191], v[172:175], v[22:25]
	v_mfma_f32_16x16x32_bf16 v[6:9], v[188:191], v[176:179], v[6:9]
	ds_read_b128 v[188:191], v197 offset:18432
	v_mfma_f32_16x16x32_bf16 v[50:53], v[192:195], v[164:167], v[50:53]
	v_mfma_f32_16x16x32_bf16 v[34:37], v[192:195], v[168:171], v[34:37]
	v_mfma_f32_16x16x32_bf16 v[18:21], v[192:195], v[172:175], v[18:21]
	v_mfma_f32_16x16x32_bf16 v[2:5], v[192:195], v[176:179], v[2:5]
	ds_read_b128 v[192:195], v197 offset:19456
	s_sub_i32 s5, s5, 1
	s_cmp_lg_u32 s5, 0
	s_cbranch_scc1 .Lpipe_mlp1
	v_add_u32_e32 v160, s11, v143
	ds_read_b128 v[164:167], v160 offset:4096
	ds_read_b128 v[168:171], v160 offset:5120
	ds_read_b128 v[172:175], v160 offset:6144
	ds_read_b128 v[176:179], v160 offset:7168
	s_add_i32 s12, s11, 0xffffa000
	s_cmp_eq_u32 s11, 0
	s_cselect_b32 s12, 0xc000, s12
	s_add_i32 s13, s12, s14
	s_add_i32 s12, s12, s4
	s_mov_b32 m0, s13
	s_waitcnt lgkmcnt(7)
	v_mfma_f32_16x16x32_bf16 v[126:129], v[180:183], v[144:147], v[126:129]
	global_load_lds_dwordx4 v[198:199], off
	v_mfma_f32_16x16x32_bf16 v[110:113], v[180:183], v[148:151], v[110:113]
	v_lshl_add_u64 v[198:199], v[198:199], 0, s[98:99]
	s_add_i32 m0, s13, 0x400
	v_mfma_f32_16x16x32_bf16 v[94:97], v[180:183], v[152:155], v[94:97]
	global_load_lds_dwordx4 v[200:201], off
	v_mfma_f32_16x16x32_bf16 v[78:81], v[180:183], v[156:159], v[78:81]
	v_lshl_add_u64 v[200:201], v[200:201], 0, s[98:99]
	s_add_i32 m0, s13, 0x800
	s_waitcnt lgkmcnt(6)
	v_mfma_f32_16x16x32_bf16 v[122:125], v[184:187], v[144:147], v[122:125]
	global_load_lds_dwordx4 v[202:203], off
	v_mfma_f32_16x16x32_bf16 v[106:109], v[184:187], v[148:151], v[106:109]
	v_lshl_add_u64 v[202:203], v[202:203], 0, s[98:99]
	s_add_i32 m0, s13, 0xc00
	v_mfma_f32_16x16x32_bf16 v[90:93], v[184:187], v[152:155], v[90:93]
	global_load_lds_dwordx4 v[204:205], off
	v_mfma_f32_16x16x32_bf16 v[74:77], v[184:187], v[156:159], v[74:77]
	v_lshl_add_u64 v[204:205], v[204:205], 0, s[98:99]
	s_mov_b32 m0, s12
	s_waitcnt lgkmcnt(5)
	v_mfma_f32_16x16x32_bf16 v[118:121], v[188:191], v[144:147], v[118:121]
	global_load_lds_dwordx4 v[206:207], off
	v_mfma_f32_16x16x32_bf16 v[102:105], v[188:191], v[148:151], v[102:105]
	v_lshl_add_u64 v[206:207], v[206:207], 0, 64
	s_add_i32 m0, s12, 0x400
	v_mfma_f32_16x16x32_bf16 v[86:89], v[188:191], v[152:155], v[86:89]
	global_load_lds_dwordx4 v[208:209], off
	v_mfma_f32_16x16x32_bf16 v[70:73], v[188:191], v[156:159], v[70:73]
	v_lshl_add_u64 v[208:209], v[208:209], 0, 64
	s_waitcnt lgkmcnt(4)
	v_mfma_f32_16x16x32_bf16 v[114:117], v[192:195], v[144:147], v[114:117]
	v_mfma_f32_16x16x32_bf16 v[98:101], v[192:195], v[148:151], v[98:101]
	v_mfma_f32_16x16x32_bf16 v[82:85], v[192:195], v[152:155], v[82:85]
	v_mfma_f32_16x16x32_bf16 v[66:69], v[192:195], v[156:159], v[66:69]
	s_waitcnt lgkmcnt(0)
	v_mfma_f32_16x16x32_bf16 v[62:65], v[180:183], v[164:167], v[62:65]
	v_mfma_f32_16x16x32_bf16 v[46:49], v[180:183], v[168:171], v[46:49]
	v_mfma_f32_16x16x32_bf16 v[30:33], v[180:183], v[172:175], v[30:33]
	v_mfma_f32_16x16x32_bf16 v[14:17], v[180:183], v[176:179], v[14:17]
	v_mfma_f32_16x16x32_bf16 v[58:61], v[184:187], v[164:167], v[58:61]
	v_mfma_f32_16x16x32_bf16 v[42:45], v[184:187], v[168:171], v[42:45]
	v_mfma_f32_16x16x32_bf16 v[26:29], v[184:187], v[172:175], v[26:29]
	v_mfma_f32_16x16x32_bf16 v[10:13], v[184:187], v[176:179], v[10:13]
	v_mfma_f32_16x16x32_bf16 v[54:57], v[188:191], v[164:167], v[54:57]
	v_mfma_f32_16x16x32_bf16 v[38:41], v[188:191], v[168:171], v[38:41]
	v_mfma_f32_16x16x32_bf16 v[22:25], v[188:191], v[172:175], v[22:25]
	v_mfma_f32_16x16x32_bf16 v[6:9], v[188:191], v[176:179], v[6:9]
	v_mfma_f32_16x16x32_bf16 v[50:53], v[192:195], v[164:167], v[50:53]
	v_mfma_f32_16x16x32_bf16 v[34:37], v[192:195], v[168:171], v[34:37]
	v_mfma_f32_16x16x32_bf16 v[18:21], v[192:195], v[172:175], v[18:21]
	v_mfma_f32_16x16x32_bf16 v[2:5], v[192:195], v[176:179], v[2:5]
	s_waitcnt vmcnt(6) lgkmcnt(0)
	s_barrier
	s_setprio 1
	v_add_u32_e32 v0, v140, v142
	s_waitcnt vmcnt(0)
	ds_read_b128 v[130:133], v0
	ds_read_b128 v[142:145], v0 offset:1024
	ds_read_b128 v[146:149], v0 offset:2048
	ds_read_b128 v[150:153], v0 offset:3072
	ds_read_b128 v[154:157], v0 offset:4096
	ds_read_b128 v[158:161], v0 offset:5120
	ds_read_b128 v[164:167], v0 offset:6144
	ds_read_b128 v[168:171], v0 offset:7168
	v_add_u32_e32 v212, v140, v141
	ds_read_b128 v[138:141], v212 offset:16384
	ds_read_b128 v[172:175], v212 offset:17408
	ds_read_b128 v[176:179], v212 offset:18432
	ds_read_b128 v[180:183], v212 offset:19456
	s_setprio 0
	s_waitcnt vmcnt(0) lgkmcnt(0)
	s_waitcnt lgkmcnt(3)
	v_mfma_f32_16x16x32_bf16 v[126:129], v[138:141], v[130:133], v[126:129]
	s_barrier
; DI unsigned pack2(float a, float b) { float2_t v = {a, b}; bf16x2_t r = __builtin_convertvector(v, bf16x2_t); return __builtin_bit_cast(unsigned, r); }
; template <int MI, int NI>
; DI void gemm256(f32x4 (&acc)[MI][NI], const u16* __restrict__ A, int lda, const u16* __restrict__ Bt, int ldb, int K, int m0, int n0, char* smem) {
;     ...
; #pragma unroll
;     for (int mi = 0; mi < MI; ++mi)
; #pragma unroll
;       for (int ni = 0; ni < NI; ++ni)
;         acc[mi][ni] = __builtin_amdgcn_mfma_f32_16x16x32_bf16(bfr[ni], af[mi], acc[mi][ni], 0, 0, 0);
;     st = st == 2 ? 0 : st + 1;
;   }
;   asm volatile("s_waitcnt lgkmcnt(0)" ::: "memory");
;   __builtin_amdgcn_s_barrier();
; DI void phase_mlp1(const Params& p, int l, int Mout, char* smem) {
;     ...
;     for (int mi = 0; mi < 8; mi += 2) {
;       const int m = m0 + wr * 128 + (mi + (lq & 1)) * 16 + lr;
; #pragma unroll
;       for (int ni = 0; ni < 4; ++ni) {
;         const int n = n0 + wc * 64 + ni * 16 + (lq >> 1) * 8;
;         float va[4], vb[4];
; #pragma unroll
;         for (int j = 0; j < 4; ++j) { const float a = fmaxf(acc[mi][ni][j], 0.f); va[j] = a * a; const float b = fmaxf(acc[mi + 1][ni][j], 0.f); vb[j] = b * b; }
;         *(uint4*)(U + (size_t)m * DFF + n) = widen16(make_uint2(pack2(va[0], va[1]), pack2(va[2], va[3])), make_uint2(pack2(vb[0], vb[1]), pack2(vb[2], vb[3])));
	s_waitcnt lgkmcnt(2)
	v_mfma_f32_16x16x32_bf16 v[122:125], v[172:175], v[130:133], v[122:125]
	s_waitcnt lgkmcnt(1)
	v_mfma_f32_16x16x32_bf16 v[184:187], v[176:179], v[130:133], v[118:121]
	s_waitcnt lgkmcnt(0)
	v_mfma_f32_16x16x32_bf16 v[114:117], v[180:183], v[130:133], v[114:117]
	v_mfma_f32_16x16x32_bf16 v[130:133], v[138:141], v[142:145], v[110:113]
	v_mfma_f32_16x16x32_bf16 v[106:109], v[172:175], v[142:145], v[106:109]
	v_mfma_f32_16x16x32_bf16 v[188:191], v[176:179], v[142:145], v[102:105]
	v_mfma_f32_16x16x32_bf16 v[98:101], v[180:183], v[142:145], v[98:101]
	v_mfma_f32_16x16x32_bf16 v[94:97], v[138:141], v[146:149], v[94:97]
	v_mfma_f32_16x16x32_bf16 v[90:93], v[172:175], v[146:149], v[90:93]
	v_mfma_f32_16x16x32_bf16 v[142:145], v[176:179], v[146:149], v[86:89]
	v_mfma_f32_16x16x32_bf16 v[82:85], v[180:183], v[146:149], v[82:85]
	v_mfma_f32_16x16x32_bf16 v[146:149], v[138:141], v[150:153], v[78:81]
	v_mfma_f32_16x16x32_bf16 v[74:77], v[172:175], v[150:153], v[74:77]
	v_mfma_f32_16x16x32_bf16 v[192:195], v[176:179], v[150:153], v[70:73]
	v_mfma_f32_16x16x32_bf16 v[66:69], v[180:183], v[150:153], v[66:69]
	v_mfma_f32_16x16x32_bf16 v[62:65], v[138:141], v[154:157], v[62:65]
	v_mfma_f32_16x16x32_bf16 v[58:61], v[172:175], v[154:157], v[58:61]
	v_mfma_f32_16x16x32_bf16 v[150:153], v[176:179], v[154:157], v[54:57]
	v_mfma_f32_16x16x32_bf16 v[50:53], v[180:183], v[154:157], v[50:53]
	v_mfma_f32_16x16x32_bf16 v[154:157], v[138:141], v[158:161], v[46:49]
	v_mfma_f32_16x16x32_bf16 v[42:45], v[172:175], v[158:161], v[42:45]
	v_mfma_f32_16x16x32_bf16 v[196:199], v[176:179], v[158:161], v[38:41]
	v_mfma_f32_16x16x32_bf16 v[34:37], v[180:183], v[158:161], v[34:37]
	v_mfma_f32_16x16x32_bf16 v[30:33], v[138:141], v[164:167], v[30:33]
	v_mfma_f32_16x16x32_bf16 v[26:29], v[172:175], v[164:167], v[26:29]
	v_mfma_f32_16x16x32_bf16 v[158:161], v[176:179], v[164:167], v[22:25]
	v_mfma_f32_16x16x32_bf16 v[18:21], v[180:183], v[164:167], v[18:21]
	v_mfma_f32_16x16x32_bf16 v[138:141], v[138:141], v[168:171], v[14:17]
	v_mfma_f32_16x16x32_bf16 v[10:13], v[172:175], v[168:171], v[10:13]
	v_mfma_f32_16x16x32_bf16 v[164:167], v[176:179], v[168:171], v[6:9]
	v_mfma_f32_16x16x32_bf16 v[2:5], v[180:183], v[168:171], v[2:5]
	s_setprio 1
	s_nop 0
	ds_read_b128 v[6:9], v0 offset:24576
	ds_read_b128 v[14:17], v0 offset:25600
	ds_read_b128 v[22:25], v0 offset:26624
	ds_read_b128 v[38:41], v0 offset:27648
	ds_read_b128 v[168:171], v0 offset:28672
	ds_read_b128 v[172:175], v0 offset:29696
	ds_read_b128 v[176:179], v0 offset:30720
	ds_read_b128 v[180:183], v0 offset:31744
	ds_read_b128 v[200:203], v212 offset:40960
	ds_read_b128 v[204:207], v212 offset:41984
	ds_read_b128 v[208:211], v212 offset:43008
	ds_read_b128 v[212:215], v212 offset:44032
	s_setprio 0
	s_waitcnt lgkmcnt(3)
	v_mfma_f32_16x16x32_bf16 v[216:219], v[200:203], v[6:9], v[126:129]
	v_mov_b32_e32 v0, v136
	s_waitcnt lgkmcnt(0)
	s_barrier
	s_waitcnt lgkmcnt(2)
	v_mfma_f32_16x16x32_bf16 v[118:121], v[204:207], v[6:9], v[122:125]
	v_mov_b32_e32 v126, v137
	v_mov_b32_e32 v127, v134
	v_lshlrev_b32_e32 v129, 2, v126
	v_lshlrev_b32_e32 v126, 4, v126
	v_mfma_f32_16x16x32_bf16 v[122:125], v[200:203], v[14:17], v[130:133]
	v_mov_b32_e32 v128, v135
	v_lshlrev_b32_e32 v127, 7, v127
	v_add_u32_e32 v0, s10, v0
	v_and_b32_e32 v126, 16, v126
	v_add3_u32 v126, v0, v127, v126
	v_lshlrev_b32_e32 v128, 6, v128
	v_and_b32_e32 v129, -8, v129
	v_ashrrev_i32_e32 v127, 31, v126
	v_add3_u32 v132, v129, s9, v128
	v_lshlrev_b64 v[128:129], 13, v[126:127]
	v_max_f32_e32 v0, v216, v216
	v_mfma_f32_16x16x32_bf16 v[94:97], v[200:203], v[22:25], v[94:97]
	v_ashrrev_i32_e32 v133, 31, v132
	v_mfma_f32_16x16x32_bf16 v[86:89], v[204:207], v[22:25], v[90:93]
	s_waitcnt lgkmcnt(1)
	v_mfma_f32_16x16x32_bf16 v[78:81], v[208:211], v[22:25], v[142:145]
	s_waitcnt lgkmcnt(0)
	v_mfma_f32_16x16x32_bf16 v[70:73], v[212:215], v[22:25], v[82:85]
	v_mfma_f32_16x16x32_bf16 v[22:25], v[204:207], v[176:179], v[26:29]
	v_mfma_f32_16x16x32_bf16 v[26:29], v[200:203], v[180:183], v[138:141]
	s_nop 2
	v_lshl_add_u64 v[138:139], s[60:61], 0, v[128:129]
	v_max_f32_e32 v128, 0, v0
	v_max_f32_e32 v0, v122, v122
	v_max_f32_e32 v122, 0, v0
	v_max_f32_e32 v0, v217, v217
	v_max_f32_e32 v129, 0, v0
	v_max_f32_e32 v0, v123, v123
	v_max_f32_e32 v123, 0, v0
	v_max_f32_e32 v0, v218, v218
	v_mfma_f32_16x16x32_bf16 v[102:105], v[212:215], v[6:9], v[114:117]
	v_max_f32_e32 v130, 0, v0
	v_max_f32_e32 v0, v124, v124
	v_max_f32_e32 v124, 0, v0
	v_mfma_f32_16x16x32_bf16 v[114:117], v[204:207], v[14:17], v[106:109]
	v_max_f32_e32 v0, v219, v219
	v_max_f32_e32 v131, 0, v0
	v_max_f32_e32 v0, v125, v125
	v_max_f32_e32 v125, 0, v0
	v_max_f32_e32 v0, v118, v118
	v_max_f32_e32 v118, 0, v0
	s_nop 1
	v_max_f32_e32 v0, v114, v114
	v_pk_mul_f32 v[128:129], v[128:129], v[128:129]
	v_pk_mul_f32 v[122:123], v[122:123], v[122:123]
	v_pk_mul_f32 v[130:131], v[130:131], v[130:131]
	v_pk_mul_f32 v[124:125], v[124:125], v[124:125]
	v_max_f32_e32 v114, 0, v0
	v_max_f32_e32 v0, v119, v119
	v_cvt_pk_bf16_f32 v128, v128, v129
	v_cvt_pk_bf16_f32 v129, v130, v131
	v_cvt_pk_bf16_f32 v130, v122, v123
	v_cvt_pk_bf16_f32 v131, v124, v125
	v_lshlrev_b64 v[122:123], 1, v[132:133]
	v_max_f32_e32 v119, 0, v0
	v_max_f32_e32 v0, v115, v115
	v_mfma_f32_16x16x32_bf16 v[110:113], v[208:211], v[6:9], v[184:187]
	v_permlane16_swap_b32_e32 v128, v130
	v_permlane16_swap_b32_e32 v129, v131
	v_lshl_add_u64 v[124:125], v[138:139], 0, v[122:123]
	v_max_f32_e32 v115, 0, v0
	v_max_f32_e32 v0, v120, v120
	v_mfma_f32_16x16x32_bf16 v[106:109], v[208:211], v[14:17], v[188:191]
	flat_store_dwordx4 v[124:125], v[128:131]
; DI unsigned pack2(float a, float b) { float2_t v = {a, b}; bf16x2_t r = __builtin_convertvector(v, bf16x2_t); return __builtin_bit_cast(unsigned, r); }
; DI void phase_mlp1(const Params& p, int l, int Mout, char* smem) {
;     ...
;     for (int mi = 0; mi < 8; mi += 2) {
;       const int m = m0 + wr * 128 + (mi + (lq & 1)) * 16 + lr;
; #pragma unroll
;       for (int ni = 0; ni < 4; ++ni) {
;         const int n = n0 + wc * 64 + ni * 16 + (lq >> 1) * 8;
;         float va[4], vb[4];
; #pragma unroll
;         for (int j = 0; j < 4; ++j) { const float a = fmaxf(acc[mi][ni][j], 0.f); va[j] = a * a; const float b = fmaxf(acc[mi + 1][ni][j], 0.f); vb[j] = b * b; }
;         *(uint4*)(U + (size_t)m * DFF + n) = widen16(make_uint2(pack2(va[0], va[1]), pack2(va[2], va[3])), make_uint2(pack2(vb[0], vb[1]), pack2(vb[2], vb[3])));
;       }
;       __builtin_amdgcn_sched_barrier(0);
;     }
	v_pk_mul_f32 v[118:119], v[118:119], v[118:119]
	s_nop 0
	v_pk_mul_f32 v[128:129], v[114:115], v[114:115]
	v_max_f32_e32 v114, 0, v0
	v_max_f32_e32 v0, v116, v116
	v_max_f32_e32 v116, 0, v0
	v_max_f32_e32 v0, v121, v121
	v_max_f32_e32 v115, 0, v0
	v_max_f32_e32 v0, v117, v117
	v_max_f32_e32 v117, 0, v0
	v_max_f32_e32 v0, v110, v110
	v_max_f32_e32 v110, 0, v0
	v_max_f32_e32 v0, v106, v106
	v_pk_mul_f32 v[120:121], v[114:115], v[114:115]
	v_pk_mul_f32 v[130:131], v[116:117], v[116:117]
	v_max_f32_e32 v106, 0, v0
	v_max_f32_e32 v0, v111, v111
	v_cvt_pk_bf16_f32 v114, v118, v119
	v_cvt_pk_bf16_f32 v115, v120, v121
	v_cvt_pk_bf16_f32 v116, v128, v129
	v_cvt_pk_bf16_f32 v117, v130, v131
	v_max_f32_e32 v111, 0, v0
	v_max_f32_e32 v0, v107, v107
	v_permlane16_swap_b32_e32 v114, v116
	v_permlane16_swap_b32_e32 v115, v117
	v_max_f32_e32 v107, 0, v0
	v_max_f32_e32 v0, v112, v112
	v_mfma_f32_16x16x32_bf16 v[98:101], v[212:215], v[14:17], v[98:101]
	flat_store_dwordx4 v[124:125], v[114:117] offset:32
	v_pk_mul_f32 v[110:111], v[110:111], v[110:111]
	s_nop 0
	v_pk_mul_f32 v[114:115], v[106:107], v[106:107]
	v_max_f32_e32 v106, 0, v0
	v_max_f32_e32 v0, v108, v108
	v_max_f32_e32 v108, 0, v0
	v_max_f32_e32 v0, v113, v113
	v_max_f32_e32 v107, 0, v0
	v_max_f32_e32 v0, v109, v109
	v_max_f32_e32 v109, 0, v0
	v_max_f32_e32 v0, v102, v102
	v_max_f32_e32 v102, 0, v0
	v_max_f32_e32 v0, v98, v98
	v_pk_mul_f32 v[112:113], v[106:107], v[106:107]
	v_pk_mul_f32 v[116:117], v[108:109], v[108:109]
	v_max_f32_e32 v98, 0, v0
	v_max_f32_e32 v0, v103, v103
	v_cvt_pk_bf16_f32 v106, v110, v111
	v_cvt_pk_bf16_f32 v107, v112, v113
	v_cvt_pk_bf16_f32 v108, v114, v115
	v_cvt_pk_bf16_f32 v109, v116, v117
	v_max_f32_e32 v103, 0, v0
	v_max_f32_e32 v0, v99, v99
	v_permlane16_swap_b32_e32 v106, v108
	v_permlane16_swap_b32_e32 v107, v109
	v_max_f32_e32 v99, 0, v0
	v_max_f32_e32 v0, v104, v104
	flat_store_dwordx4 v[124:125], v[106:109] offset:64
	v_pk_mul_f32 v[102:103], v[102:103], v[102:103]
	v_mfma_f32_16x16x32_bf16 v[90:93], v[200:203], v[38:41], v[146:149]
	v_mul_f32_e64 v106, v98, v98
	v_mul_f32_e64 v107, v99, v99
	v_max_f32_e32 v98, 0, v0
	v_max_f32_e32 v0, v100, v100
	v_max_f32_e32 v100, 0, v0
	v_max_f32_e32 v0, v105, v105
	v_max_f32_e32 v99, 0, v0
	v_max_f32_e32 v0, v101, v101
	v_max_f32_e32 v101, 0, v0
	v_pk_mul_f32 v[104:105], v[98:99], v[98:99]
	v_pk_mul_f32 v[108:109], v[100:101], v[100:101]
	v_cvt_pk_bf16_f32 v98, v102, v103
	v_cvt_pk_bf16_f32 v99, v104, v105
	v_cvt_pk_bf16_f32 v100, v106, v107
	v_cvt_pk_bf16_f32 v101, v108, v109
	s_nop 0
	v_permlane16_swap_b32_e32 v98, v100
	v_permlane16_swap_b32_e32 v99, v101
	v_mfma_f32_16x16x32_bf16 v[82:85], v[204:207], v[38:41], v[74:77]
	flat_store_dwordx4 v[124:125], v[98:101] offset:96
	v_mfma_f32_16x16x32_bf16 v[74:77], v[208:211], v[38:41], v[192:195]
	v_mfma_f32_16x16x32_bf16 v[66:69], v[212:215], v[38:41], v[66:69]
	v_mfma_f32_16x16x32_bf16 v[62:65], v[200:203], v[168:171], v[62:65]
	v_mfma_f32_16x16x32_bf16 v[54:57], v[204:207], v[168:171], v[58:61]
	v_mfma_f32_16x16x32_bf16 v[46:49], v[208:211], v[168:171], v[150:153]
	v_mfma_f32_16x16x32_bf16 v[38:41], v[212:215], v[168:171], v[50:53]
	v_mfma_f32_16x16x32_bf16 v[58:61], v[200:203], v[172:175], v[154:157]
	v_mfma_f32_16x16x32_bf16 v[50:53], v[204:207], v[172:175], v[42:45]
	v_mfma_f32_16x16x32_bf16 v[42:45], v[208:211], v[172:175], v[196:199]
	v_mfma_f32_16x16x32_bf16 v[34:37], v[212:215], v[172:175], v[34:37]
	v_mfma_f32_16x16x32_bf16 v[30:33], v[200:203], v[176:179], v[30:33]
	v_mfma_f32_16x16x32_bf16 v[14:17], v[208:211], v[176:179], v[158:161]
	v_mfma_f32_16x16x32_bf16 v[6:9], v[212:215], v[176:179], v[18:21]
	v_mfma_f32_16x16x32_bf16 v[18:21], v[204:207], v[180:183], v[10:13]
	v_mfma_f32_16x16x32_bf16 v[10:13], v[208:211], v[180:183], v[164:167]
	v_mfma_f32_16x16x32_bf16 v[2:5], v[212:215], v[180:183], v[2:5]
	v_max_f32_e32 v0, v94, v94
	v_max_f32_e32 v94, 0, v0
	v_max_f32_e32 v0, v90, v90
	v_max_f32_e32 v90, 0, v0
	v_max_f32_e32 v0, v95, v95
	v_max_f32_e32 v95, 0, v0
	v_max_f32_e32 v0, v91, v91
	v_max_f32_e32 v91, 0, v0
	v_max_f32_e32 v0, v96, v96
	v_pk_mul_f32 v[100:101], v[90:91], v[90:91]
	v_max_f32_e32 v90, 0, v0
	v_max_f32_e32 v0, v92, v92
	v_max_f32_e32 v92, 0, v0
	v_max_f32_e32 v0, v97, v97
	v_max_f32_e32 v91, 0, v0
	v_max_f32_e32 v0, v93, v93
	v_add_u32_e32 v98, 32, v126
	v_max_f32_e32 v93, 0, v0
	v_max_f32_e32 v0, v86, v86
	v_ashrrev_i32_e32 v99, 31, v98
	v_max_f32_e32 v86, 0, v0
	v_max_f32_e32 v0, v82, v82
	v_lshlrev_b64 v[98:99], 13, v[98:99]
	v_pk_mul_f32 v[94:95], v[94:95], v[94:95]
	v_pk_mul_f32 v[96:97], v[90:91], v[90:91]
	v_pk_mul_f32 v[102:103], v[92:93], v[92:93]
	v_max_f32_e32 v82, 0, v0
	v_max_f32_e32 v0, v87, v87
	v_lshl_add_u64 v[98:99], s[60:61], 0, v[98:99]
	v_cvt_pk_bf16_f32 v90, v94, v95
	v_cvt_pk_bf16_f32 v91, v96, v97
	v_cvt_pk_bf16_f32 v92, v100, v101
	v_cvt_pk_bf16_f32 v93, v102, v103
	v_max_f32_e32 v87, 0, v0
	v_max_f32_e32 v0, v83, v83
	v_permlane16_swap_b32_e32 v90, v92
	v_permlane16_swap_b32_e32 v91, v93
	v_lshl_add_u64 v[94:95], v[98:99], 0, v[122:123]
	v_max_f32_e32 v83, 0, v0
	v_max_f32_e32 v0, v88, v88
	flat_store_dwordx4 v[94:95], v[90:93]
	v_pk_mul_f32 v[86:87], v[86:87], v[86:87]
	s_nop 0
	v_pk_mul_f32 v[90:91], v[82:83], v[82:83]
	v_max_f32_e32 v82, 0, v0
	v_max_f32_e32 v0, v84, v84
	v_max_f32_e32 v84, 0, v0
	v_max_f32_e32 v0, v89, v89
	v_max_f32_e32 v83, 0, v0
	v_max_f32_e32 v0, v85, v85
	v_max_f32_e32 v85, 0, v0
	v_max_f32_e32 v0, v78, v78
	v_max_f32_e32 v78, 0, v0
	v_max_f32_e32 v0, v74, v74
	v_pk_mul_f32 v[88:89], v[82:83], v[82:83]
	v_pk_mul_f32 v[92:93], v[84:85], v[84:85]
	v_max_f32_e32 v74, 0, v0
	v_max_f32_e32 v0, v79, v79
; DI unsigned pack2(float a, float b) { float2_t v = {a, b}; bf16x2_t r = __builtin_convertvector(v, bf16x2_t); return __builtin_bit_cast(unsigned, r); }
; DI void phase_mlp1(const Params& p, int l, int Mout, char* smem) {
;     ...
;     for (int mi = 0; mi < 8; mi += 2) {
;       const int m = m0 + wr * 128 + (mi + (lq & 1)) * 16 + lr;
; #pragma unroll
;       for (int ni = 0; ni < 4; ++ni) {
;         const int n = n0 + wc * 64 + ni * 16 + (lq >> 1) * 8;
;         float va[4], vb[4];
; #pragma unroll
;         for (int j = 0; j < 4; ++j) { const float a = fmaxf(acc[mi][ni][j], 0.f); va[j] = a * a; const float b = fmaxf(acc[mi + 1][ni][j], 0.f); vb[j] = b * b; }
;         *(uint4*)(U + (size_t)m * DFF + n) = widen16(make_uint2(pack2(va[0], va[1]), pack2(va[2], va[3])), make_uint2(pack2(vb[0], vb[1]), pack2(vb[2], vb[3])));
;       }
;       __builtin_amdgcn_sched_barrier(0);
;     }
	v_cvt_pk_bf16_f32 v82, v86, v87
	v_cvt_pk_bf16_f32 v83, v88, v89
	v_cvt_pk_bf16_f32 v84, v90, v91
	v_cvt_pk_bf16_f32 v85, v92, v93
	v_max_f32_e32 v79, 0, v0
	v_max_f32_e32 v0, v75, v75
	v_permlane16_swap_b32_e32 v82, v84
	v_permlane16_swap_b32_e32 v83, v85
	v_max_f32_e32 v75, 0, v0
	v_max_f32_e32 v0, v80, v80
	flat_store_dwordx4 v[94:95], v[82:85] offset:32
	v_pk_mul_f32 v[78:79], v[78:79], v[78:79]
	s_nop 0
	v_pk_mul_f32 v[82:83], v[74:75], v[74:75]
	v_max_f32_e32 v74, 0, v0
	v_max_f32_e32 v0, v76, v76
	v_max_f32_e32 v76, 0, v0
	v_max_f32_e32 v0, v81, v81
	v_max_f32_e32 v75, 0, v0
	v_max_f32_e32 v0, v77, v77
	v_max_f32_e32 v77, 0, v0
	v_max_f32_e32 v0, v70, v70
	v_max_f32_e32 v70, 0, v0
	v_max_f32_e32 v0, v66, v66
	v_pk_mul_f32 v[80:81], v[74:75], v[74:75]
	v_pk_mul_f32 v[84:85], v[76:77], v[76:77]
	v_max_f32_e32 v66, 0, v0
	v_max_f32_e32 v0, v71, v71
	v_cvt_pk_bf16_f32 v74, v78, v79
	v_cvt_pk_bf16_f32 v75, v80, v81
	v_cvt_pk_bf16_f32 v76, v82, v83
	v_cvt_pk_bf16_f32 v77, v84, v85
	v_max_f32_e32 v71, 0, v0
	v_max_f32_e32 v0, v67, v67
	v_permlane16_swap_b32_e32 v74, v76
	v_permlane16_swap_b32_e32 v75, v77
	v_max_f32_e32 v67, 0, v0
	v_max_f32_e32 v0, v72, v72
	flat_store_dwordx4 v[94:95], v[74:77] offset:64
	v_pk_mul_f32 v[70:71], v[70:71], v[70:71]
	s_nop 0
	v_pk_mul_f32 v[74:75], v[66:67], v[66:67]
	v_max_f32_e32 v66, 0, v0
	v_max_f32_e32 v0, v68, v68
	v_max_f32_e32 v68, 0, v0
	v_max_f32_e32 v0, v73, v73
	v_max_f32_e32 v67, 0, v0
	v_max_f32_e32 v0, v69, v69
	v_max_f32_e32 v69, 0, v0
	v_pk_mul_f32 v[72:73], v[66:67], v[66:67]
	v_pk_mul_f32 v[76:77], v[68:69], v[68:69]
	v_cvt_pk_bf16_f32 v66, v70, v71
	v_cvt_pk_bf16_f32 v67, v72, v73
	v_cvt_pk_bf16_f32 v68, v74, v75
	v_cvt_pk_bf16_f32 v69, v76, v77
	s_nop 0
	v_permlane16_swap_b32_e32 v66, v68
	v_permlane16_swap_b32_e32 v67, v69
	flat_store_dwordx4 v[94:95], v[66:69] offset:96
	v_max_f32_e32 v0, v62, v62
	v_max_f32_e32 v62, 0, v0
	v_max_f32_e32 v0, v58, v58
	v_max_f32_e32 v58, 0, v0
	v_max_f32_e32 v0, v63, v63
	v_max_f32_e32 v63, 0, v0
	v_max_f32_e32 v0, v59, v59
	v_max_f32_e32 v59, 0, v0
	v_max_f32_e32 v0, v64, v64
	v_pk_mul_f32 v[68:69], v[58:59], v[58:59]
	v_max_f32_e32 v58, 0, v0
	v_max_f32_e32 v0, v60, v60
	v_max_f32_e32 v60, 0, v0
	v_max_f32_e32 v0, v65, v65
	v_max_f32_e32 v59, 0, v0
	v_max_f32_e32 v0, v61, v61
	v_add_u32_e32 v66, 64, v126
	v_max_f32_e32 v61, 0, v0
	v_max_f32_e32 v0, v54, v54
	v_ashrrev_i32_e32 v67, 31, v66
	v_max_f32_e32 v54, 0, v0
	v_max_f32_e32 v0, v50, v50
	v_lshlrev_b64 v[66:67], 13, v[66:67]
	v_pk_mul_f32 v[62:63], v[62:63], v[62:63]
	v_pk_mul_f32 v[64:65], v[58:59], v[58:59]
	v_pk_mul_f32 v[70:71], v[60:61], v[60:61]
	v_max_f32_e32 v50, 0, v0
	v_max_f32_e32 v0, v55, v55
	v_lshl_add_u64 v[66:67], s[60:61], 0, v[66:67]
	v_cvt_pk_bf16_f32 v58, v62, v63
	v_cvt_pk_bf16_f32 v59, v64, v65
	v_cvt_pk_bf16_f32 v60, v68, v69
	v_cvt_pk_bf16_f32 v61, v70, v71
	v_max_f32_e32 v55, 0, v0
	v_max_f32_e32 v0, v51, v51
	v_permlane16_swap_b32_e32 v58, v60
	v_permlane16_swap_b32_e32 v59, v61
	v_lshl_add_u64 v[62:63], v[66:67], 0, v[122:123]
	v_max_f32_e32 v51, 0, v0
	v_max_f32_e32 v0, v56, v56
	flat_store_dwordx4 v[62:63], v[58:61]
	v_pk_mul_f32 v[54:55], v[54:55], v[54:55]
	s_nop 0
	v_pk_mul_f32 v[58:59], v[50:51], v[50:51]
	v_max_f32_e32 v50, 0, v0
	v_max_f32_e32 v0, v52, v52
	v_max_f32_e32 v52, 0, v0
	v_max_f32_e32 v0, v57, v57
	v_max_f32_e32 v51, 0, v0
	v_max_f32_e32 v0, v53, v53
	v_max_f32_e32 v53, 0, v0
	v_max_f32_e32 v0, v46, v46
	v_max_f32_e32 v46, 0, v0
	v_max_f32_e32 v0, v42, v42
	v_pk_mul_f32 v[56:57], v[50:51], v[50:51]
	v_pk_mul_f32 v[60:61], v[52:53], v[52:53]
	v_max_f32_e32 v42, 0, v0
	v_max_f32_e32 v0, v47, v47
	v_cvt_pk_bf16_f32 v50, v54, v55
	v_cvt_pk_bf16_f32 v51, v56, v57
	v_cvt_pk_bf16_f32 v52, v58, v59
	v_cvt_pk_bf16_f32 v53, v60, v61
	v_max_f32_e32 v47, 0, v0
	v_max_f32_e32 v0, v43, v43
	v_permlane16_swap_b32_e32 v50, v52
	v_permlane16_swap_b32_e32 v51, v53
	v_max_f32_e32 v43, 0, v0
	v_max_f32_e32 v0, v48, v48
	flat_store_dwordx4 v[62:63], v[50:53] offset:32
	v_pk_mul_f32 v[46:47], v[46:47], v[46:47]
	s_nop 0
	v_pk_mul_f32 v[50:51], v[42:43], v[42:43]
	v_max_f32_e32 v42, 0, v0
	v_max_f32_e32 v0, v44, v44
	v_max_f32_e32 v44, 0, v0
	v_max_f32_e32 v0, v49, v49
	v_max_f32_e32 v43, 0, v0
	v_max_f32_e32 v0, v45, v45
	v_max_f32_e32 v45, 0, v0
	v_max_f32_e32 v0, v38, v38
	v_max_f32_e32 v38, 0, v0
	v_max_f32_e32 v0, v34, v34
	v_pk_mul_f32 v[48:49], v[42:43], v[42:43]
	v_pk_mul_f32 v[52:53], v[44:45], v[44:45]
	v_max_f32_e32 v34, 0, v0
	v_max_f32_e32 v0, v39, v39
	v_cvt_pk_bf16_f32 v42, v46, v47
	v_cvt_pk_bf16_f32 v43, v48, v49
	v_cvt_pk_bf16_f32 v44, v50, v51
; DI unsigned pack2(float a, float b) { float2_t v = {a, b}; bf16x2_t r = __builtin_convertvector(v, bf16x2_t); return __builtin_bit_cast(unsigned, r); }
; #define EPI_BEGIN const int lr1_ = launder_v(lr), lq1_ = launder_v(lq), wr1_ = launder_v(wr), wc1_ = launder_v(wc); { const int lr = lr1_, lq = lq1_, wr = wr1_, wc = wc1_; (void)lr; (void)lq; (void)wr; (void)wc;
; DI void phase_mlp1(const Params& p, int l, int Mout, char* smem) {
;     ...
;   for (int it = 0;; ++it) {
;     int tm, tn;
;     if (!tile_map(it, ntm, 32, blk__, gridDim.x, tm, tn)) break;
;     const int m0 = tm * 256, n0 = tn * 128;
;     f32x4 acc[8][4]; zero_accm<8, 4>(acc);
;     gemm256<8, 4>(acc, hb, 1024, (const u16*)(wl + WO_W1), 1024, 1024, m0, n0, smem);
;     EPI_BEGIN
; #pragma unroll
;     for (int mi = 0; mi < 8; mi += 2) {
;       const int m = m0 + wr * 128 + (mi + (lq & 1)) * 16 + lr;
; #pragma unroll
;       for (int ni = 0; ni < 4; ++ni) {
;         const int n = n0 + wc * 64 + ni * 16 + (lq >> 1) * 8;
;         float va[4], vb[4];
; #pragma unroll
;         for (int j = 0; j < 4; ++j) { const float a = fmaxf(acc[mi][ni][j], 0.f); va[j] = a * a; const float b = fmaxf(acc[mi + 1][ni][j], 0.f); vb[j] = b * b; }
;         *(uint4*)(U + (size_t)m * DFF + n) = widen16(make_uint2(pack2(va[0], va[1]), pack2(va[2], va[3])), make_uint2(pack2(vb[0], vb[1]), pack2(vb[2], vb[3])));
;       }
;       __builtin_amdgcn_sched_barrier(0);
;     }
	v_cvt_pk_bf16_f32 v45, v52, v53
	v_max_f32_e32 v39, 0, v0
	v_max_f32_e32 v0, v35, v35
	v_permlane16_swap_b32_e32 v42, v44
	v_permlane16_swap_b32_e32 v43, v45
	v_max_f32_e32 v35, 0, v0
	v_max_f32_e32 v0, v40, v40
	flat_store_dwordx4 v[62:63], v[42:45] offset:64
	v_pk_mul_f32 v[38:39], v[38:39], v[38:39]
	s_nop 0
	v_pk_mul_f32 v[42:43], v[34:35], v[34:35]
	v_max_f32_e32 v34, 0, v0
	v_max_f32_e32 v0, v36, v36
	v_max_f32_e32 v36, 0, v0
	v_max_f32_e32 v0, v41, v41
	v_max_f32_e32 v35, 0, v0
	v_max_f32_e32 v0, v37, v37
	v_max_f32_e32 v37, 0, v0
	v_pk_mul_f32 v[40:41], v[34:35], v[34:35]
	v_pk_mul_f32 v[44:45], v[36:37], v[36:37]
	v_cvt_pk_bf16_f32 v34, v38, v39
	v_cvt_pk_bf16_f32 v35, v40, v41
	v_cvt_pk_bf16_f32 v36, v42, v43
	v_cvt_pk_bf16_f32 v37, v44, v45
	s_nop 0
	v_permlane16_swap_b32_e32 v34, v36
	v_permlane16_swap_b32_e32 v35, v37
	flat_store_dwordx4 v[62:63], v[34:37] offset:96
	v_max_f32_e32 v0, v30, v30
	v_max_f32_e32 v30, 0, v0
	v_max_f32_e32 v0, v26, v26
	v_max_f32_e32 v26, 0, v0
	v_max_f32_e32 v0, v31, v31
	v_max_f32_e32 v31, 0, v0
	v_max_f32_e32 v0, v27, v27
	v_max_f32_e32 v27, 0, v0
	v_max_f32_e32 v0, v32, v32
	v_pk_mul_f32 v[36:37], v[26:27], v[26:27]
	v_max_f32_e32 v26, 0, v0
	v_max_f32_e32 v0, v28, v28
	v_max_f32_e32 v28, 0, v0
	v_max_f32_e32 v0, v33, v33
	v_max_f32_e32 v27, 0, v0
	v_max_f32_e32 v0, v29, v29
	v_add_u32_e32 v34, 0x60, v126
	v_max_f32_e32 v29, 0, v0
	v_max_f32_e32 v0, v22, v22
	v_ashrrev_i32_e32 v35, 31, v34
	v_max_f32_e32 v22, 0, v0
	v_max_f32_e32 v0, v18, v18
	v_lshlrev_b64 v[34:35], 13, v[34:35]
	v_pk_mul_f32 v[30:31], v[30:31], v[30:31]
	v_pk_mul_f32 v[32:33], v[26:27], v[26:27]
	v_pk_mul_f32 v[38:39], v[28:29], v[28:29]
	v_max_f32_e32 v18, 0, v0
	v_max_f32_e32 v0, v23, v23
	v_lshl_add_u64 v[34:35], s[60:61], 0, v[34:35]
	v_cvt_pk_bf16_f32 v26, v30, v31
	v_cvt_pk_bf16_f32 v27, v32, v33
	v_cvt_pk_bf16_f32 v28, v36, v37
	v_cvt_pk_bf16_f32 v29, v38, v39
	v_max_f32_e32 v23, 0, v0
	v_max_f32_e32 v0, v19, v19
	v_permlane16_swap_b32_e32 v26, v28
	v_permlane16_swap_b32_e32 v27, v29
	v_lshl_add_u64 v[30:31], v[34:35], 0, v[122:123]
	v_max_f32_e32 v19, 0, v0
	v_max_f32_e32 v0, v24, v24
	flat_store_dwordx4 v[30:31], v[26:29]
	v_pk_mul_f32 v[22:23], v[22:23], v[22:23]
	s_nop 0
	v_pk_mul_f32 v[26:27], v[18:19], v[18:19]
	v_max_f32_e32 v18, 0, v0
	v_max_f32_e32 v0, v20, v20
	v_max_f32_e32 v20, 0, v0
	v_max_f32_e32 v0, v25, v25
	v_max_f32_e32 v19, 0, v0
	v_max_f32_e32 v0, v21, v21
	v_max_f32_e32 v21, 0, v0
	v_max_f32_e32 v0, v14, v14
	v_max_f32_e32 v14, 0, v0
	v_max_f32_e32 v0, v10, v10
	v_pk_mul_f32 v[24:25], v[18:19], v[18:19]
	v_pk_mul_f32 v[28:29], v[20:21], v[20:21]
	v_max_f32_e32 v10, 0, v0
	v_max_f32_e32 v0, v15, v15
	v_cvt_pk_bf16_f32 v18, v22, v23
	v_cvt_pk_bf16_f32 v19, v24, v25
	v_cvt_pk_bf16_f32 v20, v26, v27
	v_cvt_pk_bf16_f32 v21, v28, v29
	v_max_f32_e32 v15, 0, v0
	v_max_f32_e32 v0, v11, v11
	v_permlane16_swap_b32_e32 v18, v20
	v_permlane16_swap_b32_e32 v19, v21
	v_max_f32_e32 v11, 0, v0
	v_max_f32_e32 v0, v16, v16
	flat_store_dwordx4 v[30:31], v[18:21] offset:32
	v_pk_mul_f32 v[14:15], v[14:15], v[14:15]
	s_nop 0
	v_pk_mul_f32 v[18:19], v[10:11], v[10:11]
	v_max_f32_e32 v10, 0, v0
	v_max_f32_e32 v0, v12, v12
	v_max_f32_e32 v12, 0, v0
	v_max_f32_e32 v0, v17, v17
	v_max_f32_e32 v11, 0, v0
	v_max_f32_e32 v0, v13, v13
	v_max_f32_e32 v13, 0, v0
	v_max_f32_e32 v0, v6, v6
	v_max_f32_e32 v6, 0, v0
	v_max_f32_e32 v0, v2, v2
	v_pk_mul_f32 v[16:17], v[10:11], v[10:11]
	v_pk_mul_f32 v[20:21], v[12:13], v[12:13]
	v_max_f32_e32 v2, 0, v0
	v_max_f32_e32 v0, v7, v7
	v_cvt_pk_bf16_f32 v10, v14, v15
	v_cvt_pk_bf16_f32 v11, v16, v17
	v_cvt_pk_bf16_f32 v12, v18, v19
	v_cvt_pk_bf16_f32 v13, v20, v21
	v_max_f32_e32 v7, 0, v0
	v_max_f32_e32 v0, v3, v3
	v_permlane16_swap_b32_e32 v10, v12
	v_permlane16_swap_b32_e32 v11, v13
	v_max_f32_e32 v3, 0, v0
	v_max_f32_e32 v0, v8, v8
	flat_store_dwordx4 v[30:31], v[10:13] offset:64
	v_pk_mul_f32 v[6:7], v[6:7], v[6:7]
	s_nop 0
	v_pk_mul_f32 v[10:11], v[2:3], v[2:3]
	v_max_f32_e32 v2, 0, v0
	v_max_f32_e32 v0, v4, v4
	v_max_f32_e32 v4, 0, v0
	v_max_f32_e32 v0, v9, v9
	v_max_f32_e32 v3, 0, v0
	v_max_f32_e32 v0, v5, v5
	v_max_f32_e32 v5, 0, v0
	v_pk_mul_f32 v[8:9], v[2:3], v[2:3]
	v_pk_mul_f32 v[12:13], v[4:5], v[4:5]
	v_cvt_pk_bf16_f32 v2, v6, v7
	v_cvt_pk_bf16_f32 v3, v8, v9
	v_cvt_pk_bf16_f32 v4, v10, v11
	v_cvt_pk_bf16_f32 v5, v12, v13
	s_nop 0
	v_permlane16_swap_b32_e32 v2, v4
	v_permlane16_swap_b32_e32 v3, v5
	flat_store_dwordx4 v[30:31], v[2:5] offset:96
	s_add_i32 s8, s8, 1
	s_mul_i32 s4, s8, s39
	s_add_i32 s9, s4, s6
	v_readlane_b32 s4, v253, 41
	s_cmp_ge_i32 s9, s4
	s_cbranch_scc0 .LBB0_441

; DI unsigned pack2(float a, float b) { float2_t v = {a, b}; bf16x2_t r = __builtin_convertvector(v, bf16x2_t); return __builtin_bit_cast(unsigned, r); }
; #define LAUNDER_IDS const int tid__ = launder_v((int)threadIdx.x); const int blk__ = launder_s((int)blockIdx.x); (void)tid__; (void)blk__;
; DI void phase_norm(const float* xl, const float* xc, const float* tab  , u16* hb, int M) {
;   LAUNDER_IDS
;   const int wave = tid__ >> 6, lane = tid__ & 63;
;   const int nw = gridDim.x * 4, rpw = (M + nw - 1) / nw;
;   const int rbeg = (blk__ * 4 + wave) * rpw, rend = min(rbeg + rpw, M);
;   int cur_b9 = -1;
;   float4 g[4], sh[4];
; #pragma unroll
;   for (int i = 0; i < 4; ++i) { g[i] = make_float4(0.f, 0.f, 0.f, 0.f); sh[i] = g[i]; }
;   float4 vn[4];
;   if (rbeg < rend) {
;     const float* xp0 = xrow(xl, xc, rbeg);
; #pragma unroll
;     for (int i = 0; i < 4; ++i) vn[i] = *(const float4*)(xp0 + i * 256 + lane * 4);
;   }
;   for (int r = rbeg; r < rend; ++r) {
;     const int b9 = r < NTL ? r >> 12 : 8;
;     float4 v[4];
; #pragma unroll
;     for (int i = 0; i < 4; ++i) v[i] = vn[i];
;     {
;       const float* xpn = xrow(xl, xc, min(r + 1, rend - 1));
; #pragma unroll
;       for (int i = 0; i < 4; ++i) vn[i] = *(const float4*)(xpn + i * 256 + lane * 4);
;     }
;     if (b9 != cur_b9) {
;       cur_b9 = b9;
;       const float* t = tab + b9 * 2048;
; #pragma unroll
;       for (int i = 0; i < 4; ++i) { g[i] = *(const float4*)(t + i * 256 + lane * 4); sh[i] = *(const float4*)(t + 1024 + i * 256 + lane * 4); }
;     }
;     float s = 0.f;
; #pragma unroll
;     for (int i = 0; i < 4; ++i) s += v[i].x * v[i].x + v[i].y * v[i].y + v[i].z * v[i].z + v[i].w * v[i].w;
;     s = wavesum(s);
;     const float rs = rsqrtf(s * (1.f / 1024.f) + 1e-6f);
; #pragma unroll
;     for (int i = 0; i < 4; ++i) {
;       const int k = i * 256 + lane * 4;
;       *(uint2*)(hb + (size_t)r * 1024 + k) = make_uint2(pack2(v[i].x * rs * g[i].x + sh[i].x, v[i].y * rs * g[i].y + sh[i].y), pack2(v[i].z * rs * g[i].z + sh[i].z, v[i].w * rs * g[i].w + sh[i].w));
;     }
;   }
.LBB0_451:
	s_mov_b64 s[6:7], 0
	v_writelane_b32 v255, s6, 9
	s_nop 1
	v_writelane_b32 v255, s7, 10
	s_cbranch_execz .LBB0_458
	v_mov_b32_e32 v18, v163
	s_mov_b32 s4, s2
	s_nop 0
	v_ashrrev_i32_e32 v0, 6, v18
	v_lshl_add_u32 v0, s4, 2, v0
	v_readlane_b32 s4, v254, 56
	s_nop 1
	v_mul_lo_u32 v66, v0, s4
	v_add_u32_e32 v0, s4, v66
	v_readlane_b32 s4, v253, 48
	s_nop 1
	v_min_i32_e32 v69, s4, v0
	v_cmp_lt_i32_e32 vcc, v66, v69
	s_and_saveexec_b64 s[4:5], vcc
	s_cbranch_execz .LBB0_457
	v_add_u32_e32 v0, 0xffff8000, v66
	v_cmp_gt_i32_e32 vcc, s58, v66
	s_waitcnt vmcnt(0)
	v_mov_b32_e32 v4, s49
	v_ashrrev_i32_e32 v67, 31, v66
	v_cndmask_b32_e32 v2, v0, v66, vcc
	v_mov_b32_e32 v0, s95
	v_cndmask_b32_e32 v5, v0, v4, vcc
	v_mov_b32_e32 v0, s94
	v_mov_b32_e32 v4, s48
	v_cndmask_b32_e32 v3, 0, v67, vcc
	v_cndmask_b32_e32 v4, v0, v4, vcc
	v_lshlrev_b32_e32 v0, 2, v18
	v_lshlrev_b64 v[2:3], 12, v[2:3]
	v_and_b32_e32 v68, 0xfc, v0
	v_lshl_add_u64 v[2:3], v[4:5], 0, v[2:3]
	v_lshlrev_b32_e32 v0, 2, v68
	v_lshl_add_u64 v[14:15], v[2:3], 0, v[0:1]
	flat_load_dwordx4 v[2:5], v[14:15]
	flat_load_dwordx4 v[6:9], v[14:15] offset:1024
	flat_load_dwordx4 v[10:13], v[14:15] offset:2048
	s_nop 0
	flat_load_dwordx4 v[14:17], v[14:15] offset:3072
	v_lshrrev_b32_e32 v20, 1, v66
	v_mov_b32_e32 v21, 0
	v_lshlrev_b64 v[20:21], 12, v[20:21]
	v_and_b32_e32 v0, 1, v66
	v_lshl_or_b32 v20, v0, 6, v20
	v_bfe_u32 v0, v18, 3, 3
	v_lshl_or_b32 v20, v0, 7, v20
	v_and_b32_e32 v0, 7, v18
	v_readlane_b32 s6, v253, 39
	v_lshl_or_b32 v20, v0, 3, v20
	v_readlane_b32 s7, v253, 40
	v_mov_b32_e32 v0, v1
	v_mov_b32_e32 v73, -1
	v_add_u32_e32 v72, -1, v69
	v_lshl_add_u64 v[70:71], s[6:7], 0, v[20:21]
	s_mov_b64 s[6:7], 0
	v_mov_b64_e32 v[44:45], v[0:1]
	s_waitcnt lgkmcnt(0)
	v_mov_b64_e32 v[42:43], v[0:1]
	v_mov_b64_e32 v[32:33], v[0:1]
	v_mov_b64_e32 v[30:31], v[0:1]
	v_mov_b64_e32 v[28:29], v[0:1]
	v_mov_b64_e32 v[26:27], v[0:1]
	v_mov_b64_e32 v[40:41], v[0:1]
	v_mov_b64_e32 v[38:39], v[0:1]
	v_mov_b64_e32 v[18:19], v[0:1]
	v_mov_b64_e32 v[20:21], v[0:1]
	v_mov_b64_e32 v[22:23], v[0:1]
	v_mov_b64_e32 v[24:25], v[0:1]
	v_mov_b64_e32 v[34:35], v[0:1]
	v_mov_b64_e32 v[36:37], v[0:1]
	v_mov_b64_e32 v[46:47], v[0:1]
	v_mov_b64_e32 v[48:49], v[0:1]
	s_branch .LBB0_455
.LBB0_454:
	s_or_b64 exec, exec, s[8:9]
	s_waitcnt vmcnt(0) lgkmcnt(0)
	v_pk_mul_f32 v[74:75], v[2:3], v[2:3]
	v_pk_mul_f32 v[78:79], v[6:7], v[6:7]
	v_mov_b32_e32 v82, v14
	v_mov_b32_e32 v83, v10
	v_pk_mul_f32 v[76:77], v[4:5], v[4:5]
	v_pk_mul_f32 v[80:81], v[8:9], v[8:9]
	v_pk_mul_f32 v[82:83], v[82:83], v[82:83]
	v_mov_b32_e32 v84, v15
	v_mov_b32_e32 v85, v11
	v_add_f32_e32 v0, v75, v74
	v_add_f32_e32 v67, v79, v78
	v_pk_fma_f32 v[82:83], v[84:85], v[84:85], v[82:83]
	v_mov_b32_e32 v84, v16
	v_mov_b32_e32 v85, v12
	v_add_f32_e32 v0, v76, v0
	v_add_f32_e32 v67, v80, v67
	v_pk_fma_f32 v[82:83], v[84:85], v[84:85], v[82:83]
	v_mov_b32_e32 v84, v17
	v_mov_b32_e32 v85, v13
	v_add_f32_e32 v0, v77, v0
	v_add_f32_e32 v67, v81, v67
	v_pk_fma_f32 v[82:83], v[84:85], v[84:85], v[82:83]
	v_add_f32_e32 v0, v67, v0
	v_add_f32_e32 v0, v83, v0
	v_add_f32_e32 v0, v82, v0
	s_nop 1
	v_add_f32_dpp v0, v0, v0 row_ror:8 row_mask:0xf bank_mask:0xf bound_ctrl:1
	s_nop 1
	v_add_f32_dpp v0, v0, v0 row_ror:4 row_mask:0xf bank_mask:0xf bound_ctrl:1
	s_nop 1
	v_add_f32_dpp v0, v0, v0 row_ror:2 row_mask:0xf bank_mask:0xf bound_ctrl:1
	s_nop 1
	v_add_f32_dpp v0, v0, v0 row_ror:1 row_mask:0xf bank_mask:0xf bound_ctrl:1
	s_nop 0
	v_readlane_b32 s9, v0, 16
	v_readlane_b32 s8, v0, 0
	s_nop 0
	v_mov_b32_e32 v67, s9
	v_add_f32_e32 v67, s8, v67
	v_readlane_b32 s8, v0, 32
	s_nop 1
	v_add_f32_e32 v67, s8, v67
	v_readlane_b32 s8, v0, 48
	s_nop 1
	v_add_f32_e32 v0, s8, v67
	v_fmamk_f32 v0, v0, 0x3a800000, v162
	v_mul_f32_e32 v67, 0x4b800000, v0
	v_cmp_gt_f32_e32 vcc, s31, v0
	s_mov_b64 s[8:9], 0x800
	s_nop 0
	v_cndmask_b32_e32 v0, v0, v67, vcc
	v_rsq_f32_e32 v0, v0
	s_nop 0
	v_mul_f32_e32 v67, 0x45800000, v0
	v_cndmask_b32_e32 v0, v0, v67, vcc
	v_pk_mul_f32 v[2:3], v[2:3], v[0:1] op_sel_hi:[1,0]
	v_pk_mul_f32 v[4:5], v[4:5], v[0:1] op_sel_hi:[1,0]
	v_pk_fma_f32 v[2:3], v[18:19], v[2:3], v[38:39]
	v_pk_fma_f32 v[4:5], v[20:21], v[4:5], v[40:41]
	v_cvt_pk_bf16_f32 v2, v2, v3
	v_cvt_pk_bf16_f32 v3, v4, v5
	flat_store_dwordx2 v[70:71], v[2:3]
	v_pk_mul_f32 v[2:3], v[6:7], v[0:1] op_sel_hi:[1,0]
	v_pk_mul_f32 v[4:5], v[8:9], v[0:1] op_sel_hi:[1,0]
	v_pk_fma_f32 v[2:3], v[22:23], v[2:3], v[26:27]
	v_pk_fma_f32 v[4:5], v[24:25], v[4:5], v[28:29]
	v_cvt_pk_bf16_f32 v2, v2, v3
	v_cvt_pk_bf16_f32 v3, v4, v5
	flat_store_dwordx2 v[70:71], v[2:3] offset:1024
	v_pk_mul_f32 v[2:3], v[10:11], v[0:1] op_sel_hi:[1,0]
	v_pk_mul_f32 v[4:5], v[12:13], v[0:1] op_sel_hi:[1,0]
	v_pk_fma_f32 v[2:3], v[34:35], v[2:3], v[30:31]
	v_pk_fma_f32 v[4:5], v[36:37], v[4:5], v[32:33]
	v_cvt_pk_bf16_f32 v2, v2, v3
	v_cvt_pk_bf16_f32 v3, v4, v5
	flat_store_dwordx2 v[70:71], v[2:3] offset:2048
	v_pk_mul_f32 v[2:3], v[14:15], v[0:1] op_sel_hi:[1,0]
	v_pk_mul_f32 v[4:5], v[16:17], v[0:1] op_sel_hi:[1,0]
	v_pk_fma_f32 v[2:3], v[46:47], v[2:3], v[42:43]
	v_pk_fma_f32 v[4:5], v[48:49], v[4:5], v[44:45]
	v_cvt_pk_bf16_f32 v2, v2, v3
	v_cvt_pk_bf16_f32 v3, v4, v5
	v_cmp_ge_i32_e32 vcc, v66, v69
	flat_store_dwordx2 v[70:71], v[2:3] offset:3072
	v_and_b32_e32 v90, 1, v66
	v_mul_u32_u24_e32 v90, 0xf80, v90
	v_sub_u32_e32 v90, 0xfc0, v90
	v_mov_b32_e32 v91, 0
	v_lshl_add_u64 v[70:71], v[70:71], 0, v[90:91]
	s_or_b64 s[6:7], vcc, s[6:7]
	v_mov_b64_e32 v[4:5], v[64:65]
	v_mov_b64_e32 v[2:3], v[62:63]
	v_mov_b64_e32 v[8:9], v[60:61]
	v_mov_b64_e32 v[6:7], v[58:59]
	v_mov_b64_e32 v[12:13], v[56:57]
	v_mov_b64_e32 v[10:11], v[54:55]
	v_mov_b64_e32 v[16:17], v[52:53]
	v_mov_b64_e32 v[14:15], v[50:51]
	s_andn2_b64 exec, exec, s[6:7]
	s_cbranch_execz .LBB0_457

; __global__ void __launch_bounds__(256, 2) fwd_megakernel(Params pk) {
;   __shared__ __attribute__((aligned(16))) char smem[73728];
	.amdhsa_kernel _Z14fwd_megakernel6Params
		.amdhsa_group_segment_fixed_size 73768
		.amdhsa_private_segment_fixed_size 0
		.amdhsa_kernarg_size 544
		.amdhsa_user_sgpr_count 2
		.amdhsa_user_sgpr_dispatch_ptr 0
		.amdhsa_user_sgpr_queue_ptr 0
		.amdhsa_user_sgpr_kernarg_segment_ptr 1
		.amdhsa_user_sgpr_dispatch_id 0
		.amdhsa_user_sgpr_kernarg_preload_length 0
		.amdhsa_user_sgpr_kernarg_preload_offset 0
		.amdhsa_user_sgpr_private_segment_size 0
		.amdhsa_uses_dynamic_stack 0
		.amdhsa_enable_private_segment 0
		.amdhsa_system_sgpr_workgroup_id_x 1
		.amdhsa_system_sgpr_workgroup_id_y 0
		.amdhsa_system_sgpr_workgroup_id_z 0
		.amdhsa_system_sgpr_workgroup_info 0
		.amdhsa_system_vgpr_workitem_id 2
		.amdhsa_next_free_vgpr 256
		.amdhsa_next_free_sgpr 100
		.amdhsa_accum_offset 256
		.amdhsa_reserve_vcc 1
		.amdhsa_float_round_mode_32 0
		.amdhsa_float_round_mode_16_64 0
		.amdhsa_float_denorm_mode_32 3
		.amdhsa_float_denorm_mode_16_64 3
		.amdhsa_dx10_clamp 1
		.amdhsa_ieee_mode 1
		.amdhsa_fp16_overflow 0
		.amdhsa_tg_split 0
		.amdhsa_exception_fp_ieee_invalid_op 0
		.amdhsa_exception_fp_denorm_src 0
		.amdhsa_exception_fp_ieee_div_zero 0
		.amdhsa_exception_fp_ieee_overflow 0
		.amdhsa_exception_fp_ieee_underflow 0
		.amdhsa_exception_fp_ieee_inexact 0
		.amdhsa_exception_int_div_zero 0
	.end_amdhsa_kernel

; __global__ void __launch_bounds__(256, 2) fwd_megakernel(Params pk) {
;   __shared__ __attribute__((aligned(16))) char smem[73728];
amdhsa.kernels:
  - .agpr_count:     0
    .args:
      - .offset:         0
        .size:           288
        .value_kind:     by_value
      - .offset:         288
        .size:           4
        .value_kind:     hidden_block_count_x
      - .offset:         292
        .size:           4
        .value_kind:     hidden_block_count_y
      - .offset:         296
        .size:           4
        .value_kind:     hidden_block_count_z
      - .offset:         300
        .size:           2
        .value_kind:     hidden_group_size_x
      - .offset:         302
        .size:           2
        .value_kind:     hidden_group_size_y
      - .offset:         304
        .size:           2
        .value_kind:     hidden_group_size_z
      - .offset:         306
        .size:           2
        .value_kind:     hidden_remainder_x
      - .offset:         308
        .size:           2
        .value_kind:     hidden_remainder_y
      - .offset:         310
        .size:           2
        .value_kind:     hidden_remainder_z
      - .offset:         328
        .size:           8
        .value_kind:     hidden_global_offset_x
      - .offset:         336
        .size:           8
        .value_kind:     hidden_global_offset_y
      - .offset:         344
        .size:           8
        .value_kind:     hidden_global_offset_z
      - .offset:         352
        .size:           2
        .value_kind:     hidden_grid_dims
      - .offset:         376
        .size:           8
        .value_kind:     hidden_multigrid_sync_arg
    .group_segment_fixed_size: 73768
    .kernarg_segment_align: 8
    .kernarg_segment_size: 544
    .language:       OpenCL C
    .language_version:
      - 2
      - 0
    .max_flat_workgroup_size: 256
    .name:           _Z14fwd_megakernel6Params
    .private_segment_fixed_size: 0
    .sgpr_count:     106
    .sgpr_spill_count: 149
    .symbol:         _Z14fwd_megakernel6Params.kd
    .uniform_work_group_size: 1
    .uses_dynamic_stack: false
    .vgpr_count:     256
    .vgpr_spill_count: 0
    .wavefront_size: 64
